# strategy 9: scalar address-select block rotated off the K-loop head into the previous iteration's last MFMA block (k=1 and k=8 GEMM loops)
# baseline (speedup 1.0000x reference)
; #define PG8_STAGE(bufoff, gbase, voff) do { _Pragma("unroll") for (int _i = 0; _i < 2; ++_i) \
;         __builtin_amdgcn_global_load_lds((const unsigned*)((const char*)(gbase) + (voff)[_i]), (LAS unsigned*)(lds + (bufoff) + ldsw + _i * 8192), 16, 0, 0); } while (0)
; #define PG8_LDA(dst, b, h) do { _Pragma("unroll") for (int m = 0; m < 4; ++m) _Pragma("unroll") for (int k = 0; k < 2; ++k) dst[m][k] = *(const LAS bf16x8*)(lds + PG8_SA(b, h) + aoff + m * 2048 + k * 1024); } while (0)
; #define PG8_LDB(dst, b, h) do { _Pragma("unroll") for (int n = 0; n < 2; ++n) _Pragma("unroll") for (int k = 0; k < 2; ++k) dst[n][k] = *(const LAS bf16x8*)(lds + PG8_SB(b, h) + boff + n * 2048 + k * 1024); } while (0)
; #define PG8_WAIT_V(n) asm volatile("s_waitcnt vmcnt(" #n ")" ::: "memory")
; #define PG8_WAIT_L(n) asm volatile("s_waitcnt lgkmcnt(" #n ")" ::: "memory")
; #define PG8_BAR __builtin_amdgcn_s_barrier()
; #define PG8_SCHED __builtin_amdgcn_sched_barrier(0)
; template <class Epi, class Sched, bool ALIGN_EPI = false, bool SP2 = false>
; __device__ __forceinline__ void gemm_phase(LAS unsigned char* lds, const Gemm g, const Sched& S, const Epi& E, const int tid_) {
;     ...
;         const char* nA = has_next ? (const char*)g.A + (size_t)nxt.pm * tstep : cA; const char* nB = has_next ? (const char*)g.Bt + (size_t)nxt.pn * tstep : cB;
;         for (int t = 0; t < nt; t += 2) {
;             const bool last = (t == nt - 2);
;             const char* a1 = cA + (size_t)(t + 1) * kstep;
;             const char* a2 = last ? nA : cA + (size_t)(t + 2) * kstep; const char* b2 = last ? nB : cB + (size_t)(t + 2) * kstep;
;             const char* a3 = a2 + kstep; const char* b3 = b2 + kstep;
;             if (last && has_next) S.a_ready(nxt);
;             if constexpr (SP2) {
;             PG8_LDB(B0, 0, 0); PG8_LDB(B1, 0, 1); PG8_SCHED; PG8_LDA(At, 0, 0); PG8_STAGE(PG8_SA(1, 1), a1 + hstep, voffA);
;             PG8_WAIT_V(8); PG8_WAIT_L(0); PG8_BAR; PG8_MMA(0, 0, At, B0); PG8_MMA(0, 1, At, B1); PG8_BAR; PG8_SCHED;
;     ...
;         for (int a = 0; a < 2; ++a)
; #pragma unroll
;             for (int b = 0; b < 2; ++b)
; #pragma unroll
;                 for (int m = 0; m < 4; ++m)
; #pragma unroll
;                     for (int n = 0; n < 2; ++n) acc[a][b][m][n] = (f32x4){0.f, 0.f, 0.f, 0.f};
;         cur = nxt; cA = nA; cB = nB; ++ui;
.LBB0_33:
	s_ashr_i32 s17, s16, 31
	s_lshl_b64 s[18:19], s[16:17], 20
	s_add_u32 s18, s29, s18
	s_addc_u32 s19, s30, s19
	s_and_b64 s[42:43], s[40:41], exec
	s_cselect_b32 s17, s19, s47
	s_cselect_b32 s21, s18, s46
	s_ashr_i32 s15, s14, 31
	s_lshl_b64 s[42:43], s[14:15], 20
	s_add_u32 s42, s31, s42
	s_addc_u32 s43, s54, s43
	s_and_b64 s[50:51], s[40:41], exec
	s_cselect_b32 s15, s43, s49
	s_cselect_b32 s64, s42, s48
	s_add_u32 s46, s46, 0x80080
	s_addc_u32 s47, s47, 0
	s_add_u32 s65, s48, 0x100
	v_mov_b32_e32 v2, 0
	s_addc_u32 s66, s49, 0
	s_mov_b32 s67, -2
	v_mov_b32_e32 v3, v2
	v_mov_b64_e32 v[4:5], 0
	v_mov_b64_e32 v[6:7], 0
	v_mov_b64_e32 v[8:9], 0
	v_mov_b64_e32 v[10:11], 0
	v_mov_b64_e32 v[12:13], 0
	v_mov_b64_e32 v[14:15], 0
	v_mov_b64_e32 v[16:17], 0
	v_mov_b64_e32 v[18:19], 0
	v_mov_b64_e32 v[20:21], 0
	v_mov_b64_e32 v[22:23], 0
	v_mov_b64_e32 v[24:25], 0
	v_mov_b64_e32 v[26:27], 0
	v_mov_b64_e32 v[28:29], 0
	v_mov_b64_e32 v[30:31], 0
	v_mov_b64_e32 v[32:33], 0
	v_mov_b64_e32 v[34:35], 0
	v_mov_b64_e32 v[36:37], 0
	v_mov_b64_e32 v[38:39], 0
	v_mov_b64_e32 v[40:41], 0
	v_mov_b64_e32 v[42:43], 0
	v_mov_b64_e32 v[44:45], 0
	v_mov_b64_e32 v[46:47], 0
	v_mov_b64_e32 v[48:49], 0
	v_mov_b64_e32 v[50:51], 0
	v_mov_b64_e32 v[52:53], 0
	v_mov_b64_e32 v[54:55], 0
	v_mov_b64_e32 v[56:57], 0
	v_mov_b64_e32 v[58:59], 0
	v_mov_b64_e32 v[60:61], 0
	v_mov_b64_e32 v[62:63], 0
	v_mov_b64_e32 v[64:65], 0
	v_mov_b64_e32 v[66:67], 0
	v_mov_b64_e32 v[68:69], 0
	v_mov_b64_e32 v[70:71], 0
	v_mov_b64_e32 v[72:73], 0
	v_mov_b64_e32 v[74:75], 0
	v_mov_b64_e32 v[76:77], 0
	v_mov_b64_e32 v[78:79], 0
	v_mov_b64_e32 v[80:81], 0
	v_mov_b64_e32 v[82:83], 0
	v_mov_b64_e32 v[84:85], 0
	v_mov_b64_e32 v[86:87], 0
	v_mov_b64_e32 v[88:89], 0
	v_mov_b64_e32 v[90:91], 0
	v_mov_b64_e32 v[92:93], 0
	v_mov_b64_e32 v[94:95], 0
	v_mov_b64_e32 v[96:97], 0
	v_mov_b64_e32 v[98:99], 0
	v_mov_b64_e32 v[100:101], 0
	v_mov_b64_e32 v[102:103], 0
	v_mov_b64_e32 v[104:105], 0
	v_mov_b64_e32 v[106:107], 0
	v_mov_b64_e32 v[108:109], 0
	v_mov_b64_e32 v[110:111], 0
	v_mov_b64_e32 v[112:113], 0
	v_mov_b64_e32 v[114:115], 0
	v_mov_b64_e32 v[116:117], 0
	v_mov_b64_e32 v[118:119], 0
	v_mov_b64_e32 v[120:121], 0
	v_mov_b64_e32 v[122:123], 0
	v_mov_b64_e32 v[124:125], 0
	v_mov_b64_e32 v[126:127], 0
	v_mov_b64_e32 v[128:129], 0
	s_add_u32 s48, s46, 0xfff80080
	s_addc_u32 s49, s47, -1
	s_add_i32 s68, 0, 0x10000
	s_cmp_eq_u32 s67, 28
	s_cselect_b32 s51, s17, s49
	s_cselect_b32 s50, s21, s48
	s_cselect_b32 s49, s15, s66
	s_cselect_b32 s48, s64, s65
	s_add_i32 s70, 0, 0x14000
.LBB0_34:
	v_add_u32_e32 v140, s68, v143
	s_nop 0
	ds_read_b128 v[146:149], v140
	ds_read_b128 v[150:153], v140 offset:1024
	ds_read_b128 v[154:157], v140 offset:2048
	ds_read_b128 v[158:161], v140 offset:3072
	v_add_u32_e32 v140, s70, v143
	ds_read_b128 v[162:165], v140
	ds_read_b128 v[166:169], v140 offset:1024
	ds_read_b128 v[170:173], v140 offset:2048
	ds_read_b128 v[174:177], v140 offset:3072
	s_add_i32 m0, s45, 0xc000
	ds_read_b128 v[178:181], v145
	ds_read_b128 v[182:185], v145 offset:1024
	ds_read_b128 v[200:203], v145 offset:2048
	ds_read_b128 v[204:207], v145 offset:3072
	ds_read_b128 v[208:211], v145 offset:4096
	ds_read_b128 v[212:215], v145 offset:5120
	ds_read_b128 v[216:219], v145 offset:6144
	ds_read_b128 v[220:223], v145 offset:7168
	global_load_lds_dwordx4 v136, s[46:47]
	s_add_i32 m0, s45, 0xe000
	s_nop 0
	global_load_lds_dwordx4 v138, s[46:47]
	s_waitcnt vmcnt(8)
	s_waitcnt lgkmcnt(0)
	s_barrier
	s_waitcnt lgkmcnt(0)
	v_mfma_f32_16x16x32_bf16 v[126:129], v[146:149], v[178:181], v[126:129]
	v_mfma_f32_16x16x32_bf16 v[122:125], v[154:157], v[178:181], v[122:125]
	v_mfma_f32_16x16x32_bf16 v[110:113], v[146:149], v[200:203], v[110:113]
	v_mfma_f32_16x16x32_bf16 v[106:109], v[154:157], v[200:203], v[106:109]
	v_mfma_f32_16x16x32_bf16 v[94:97], v[146:149], v[208:211], v[94:97]
	v_mfma_f32_16x16x32_bf16 v[90:93], v[154:157], v[208:211], v[90:93]
	v_mfma_f32_16x16x32_bf16 v[78:81], v[146:149], v[216:219], v[78:81]
	v_mfma_f32_16x16x32_bf16 v[74:77], v[154:157], v[216:219], v[74:77]
	v_mfma_f32_16x16x32_bf16 v[126:129], v[150:153], v[182:185], v[126:129]
	v_mfma_f32_16x16x32_bf16 v[122:125], v[158:161], v[182:185], v[122:125]
	v_mfma_f32_16x16x32_bf16 v[110:113], v[150:153], v[204:207], v[110:113]
	v_mfma_f32_16x16x32_bf16 v[106:109], v[158:161], v[204:207], v[106:109]
	v_mfma_f32_16x16x32_bf16 v[94:97], v[150:153], v[212:215], v[94:97]
	v_mfma_f32_16x16x32_bf16 v[90:93], v[158:161], v[212:215], v[90:93]
	v_mfma_f32_16x16x32_bf16 v[78:81], v[150:153], v[220:223], v[78:81]
	v_mfma_f32_16x16x32_bf16 v[74:77], v[158:161], v[220:223], v[74:77]
	v_mfma_f32_16x16x32_bf16 v[118:121], v[162:165], v[178:181], v[118:121]
	v_mfma_f32_16x16x32_bf16 v[114:117], v[170:173], v[178:181], v[114:117]
	v_mfma_f32_16x16x32_bf16 v[102:105], v[162:165], v[200:203], v[102:105]
	v_mfma_f32_16x16x32_bf16 v[98:101], v[170:173], v[200:203], v[98:101]
	v_mfma_f32_16x16x32_bf16 v[86:89], v[162:165], v[208:211], v[86:89]
	v_mfma_f32_16x16x32_bf16 v[82:85], v[170:173], v[208:211], v[82:85]
	v_mfma_f32_16x16x32_bf16 v[70:73], v[162:165], v[216:219], v[70:73]
	v_mfma_f32_16x16x32_bf16 v[66:69], v[170:173], v[216:219], v[66:69]
	v_mfma_f32_16x16x32_bf16 v[118:121], v[166:169], v[182:185], v[118:121]
	v_mfma_f32_16x16x32_bf16 v[114:117], v[174:177], v[182:185], v[114:117]
	v_mfma_f32_16x16x32_bf16 v[102:105], v[166:169], v[204:207], v[102:105]
	v_mfma_f32_16x16x32_bf16 v[98:101], v[174:177], v[204:207], v[98:101]
	v_mfma_f32_16x16x32_bf16 v[86:89], v[166:169], v[212:215], v[86:89]
	v_mfma_f32_16x16x32_bf16 v[82:85], v[174:177], v[212:215], v[82:85]
	v_mfma_f32_16x16x32_bf16 v[70:73], v[166:169], v[220:223], v[70:73]
	v_mfma_f32_16x16x32_bf16 v[66:69], v[174:177], v[220:223], v[66:69]
	s_barrier
; #define PG8_STAGE(bufoff, gbase, voff) do { _Pragma("unroll") for (int _i = 0; _i < 2; ++_i) \
;         __builtin_amdgcn_global_load_lds((const unsigned*)((const char*)(gbase) + (voff)[_i]), (LAS unsigned*)(lds + (bufoff) + ldsw + _i * 8192), 16, 0, 0); } while (0)
; #define PG8_LDA(dst, b, h) do { _Pragma("unroll") for (int m = 0; m < 4; ++m) _Pragma("unroll") for (int k = 0; k < 2; ++k) dst[m][k] = *(const LAS bf16x8*)(lds + PG8_SA(b, h) + aoff + m * 2048 + k * 1024); } while (0)
; #define PG8_LDB(dst, b, h) do { _Pragma("unroll") for (int n = 0; n < 2; ++n) _Pragma("unroll") for (int k = 0; k < 2; ++k) dst[n][k] = *(const LAS bf16x8*)(lds + PG8_SB(b, h) + boff + n * 2048 + k * 1024); } while (0)
; #define PG8_MMA(ai, bj, At, Bt) do { __builtin_amdgcn_s_setprio(1); _Pragma("unroll") for (int m = 0; m < 4; ++m) _Pragma("unroll") for (int n = 0; n < 2; ++n) _Pragma("unroll") for (int k = 0; k < 2; ++k) \
;         acc[ai][bj][m][n] = __builtin_amdgcn_mfma_f32_16x16x32_bf16(Bt[n][k], At[m][k], acc[ai][bj][m][n], 0, 0, 0); __builtin_amdgcn_s_setprio(0); } while (0)
; #define PG8_WAIT_V(n) asm volatile("s_waitcnt vmcnt(" #n ")" ::: "memory")
; #define PG8_WAIT_L(n) asm volatile("s_waitcnt lgkmcnt(" #n ")" ::: "memory")
; #define PG8_BAR __builtin_amdgcn_s_barrier()
; #define PG8_SCHED __builtin_amdgcn_sched_barrier(0)
; template <class Epi, class Sched, bool ALIGN_EPI = false, bool SP2 = false>
; __device__ __forceinline__ void gemm_phase(LAS unsigned char* lds, const Gemm g, const Sched& S, const Epi& E, const int tid_) {
;     ...
;             PG8_LDA(At, 0, 1); PG8_STAGE(PG8_SB(0, 0), b2, voffB); PG8_STAGE(PG8_SB(0, 1), b2 + hstep, voffB); PG8_STAGE(PG8_SA(0, 0), a2, voffA);
;             PG8_WAIT_V(8); PG8_WAIT_L(0); PG8_BAR; PG8_MMA(1, 0, At, B0); PG8_MMA(1, 1, At, B1); PG8_BAR; PG8_SCHED;
;             PG8_LDB(B0, 1, 0); PG8_LDB(B1, 1, 1); PG8_SCHED; PG8_LDA(At, 1, 0); PG8_STAGE(PG8_SA(0, 1), a2 + hstep, voffA);
;             PG8_WAIT_V(8); PG8_WAIT_L(0); PG8_BAR; PG8_MMA(0, 0, At, B0); PG8_MMA(0, 1, At, B1); PG8_BAR; PG8_SCHED;
;             PG8_LDA(At, 1, 1); PG8_STAGE(PG8_SB(1, 0), b3, voffB); PG8_STAGE(PG8_SB(1, 1), b3 + hstep, voffB); PG8_STAGE(PG8_SA(1, 0), a3, voffA);
	s_add_i32 s68, s68, s55
	s_mov_b32 m0, s68
	ds_read_b128 v[178:181], v145 offset:16384
	ds_read_b128 v[182:185], v145 offset:17408
	ds_read_b128 v[200:203], v145 offset:18432
	ds_read_b128 v[204:207], v145 offset:19456
	ds_read_b128 v[208:211], v145 offset:20480
	ds_read_b128 v[212:215], v145 offset:21504
	ds_read_b128 v[216:219], v145 offset:22528
	ds_read_b128 v[220:223], v145 offset:23552
	global_load_lds_dwordx4 v0, s[48:49]
	s_add_i32 m0, s68, 0x2000
	s_add_u32 s68, s48, 0x80000
	v_lshl_add_u64 v[192:193], s[48:49], 0, v[134:135]
	s_addc_u32 s69, s49, 0
	s_add_i32 s70, s70, s55
	global_load_lds_dwordx4 v134, s[48:49]
	s_mov_b32 m0, s70
	v_lshl_add_u64 v[236:237], s[50:51], 0, v[132:133]
	global_load_lds_dwordx4 v0, s[68:69]
	s_add_i32 m0, s70, 0x2000
	s_nop 0
	global_load_lds_dwordx4 v134, s[68:69]
	v_lshl_add_u64 v[224:225], s[50:51], 0, v[130:131]
	s_mov_b32 m0, s45
	s_nop 0
	global_load_lds_dwordx4 v130, s[50:51]
	s_mov_b32 m0, s56
	s_nop 0
	global_load_lds_dwordx4 v132, s[50:51]
	s_waitcnt vmcnt(8)
	s_waitcnt lgkmcnt(0)
	s_barrier
	s_waitcnt lgkmcnt(0)
	v_mfma_f32_16x16x32_bf16 v[62:65], v[146:149], v[178:181], v[62:65]
	v_mfma_f32_16x16x32_bf16 v[58:61], v[154:157], v[178:181], v[58:61]
	v_mfma_f32_16x16x32_bf16 v[46:49], v[146:149], v[200:203], v[46:49]
	v_mfma_f32_16x16x32_bf16 v[42:45], v[154:157], v[200:203], v[42:45]
	v_mfma_f32_16x16x32_bf16 v[30:33], v[146:149], v[208:211], v[30:33]
	v_mfma_f32_16x16x32_bf16 v[26:29], v[154:157], v[208:211], v[26:29]
	v_mfma_f32_16x16x32_bf16 v[14:17], v[146:149], v[216:219], v[14:17]
	v_mfma_f32_16x16x32_bf16 v[10:13], v[154:157], v[216:219], v[10:13]
	v_mfma_f32_16x16x32_bf16 v[62:65], v[150:153], v[182:185], v[62:65]
	v_mfma_f32_16x16x32_bf16 v[58:61], v[158:161], v[182:185], v[58:61]
	v_mfma_f32_16x16x32_bf16 v[46:49], v[150:153], v[204:207], v[46:49]
	v_mfma_f32_16x16x32_bf16 v[42:45], v[158:161], v[204:207], v[42:45]
	v_mfma_f32_16x16x32_bf16 v[30:33], v[150:153], v[212:215], v[30:33]
	v_mfma_f32_16x16x32_bf16 v[26:29], v[158:161], v[212:215], v[26:29]
	v_mfma_f32_16x16x32_bf16 v[14:17], v[150:153], v[220:223], v[14:17]
	v_mfma_f32_16x16x32_bf16 v[10:13], v[158:161], v[220:223], v[10:13]
	v_mfma_f32_16x16x32_bf16 v[54:57], v[162:165], v[178:181], v[54:57]
	v_mfma_f32_16x16x32_bf16 v[50:53], v[170:173], v[178:181], v[50:53]
	v_mfma_f32_16x16x32_bf16 v[38:41], v[162:165], v[200:203], v[38:41]
	v_mfma_f32_16x16x32_bf16 v[34:37], v[170:173], v[200:203], v[34:37]
	v_mfma_f32_16x16x32_bf16 v[22:25], v[162:165], v[208:211], v[22:25]
	v_mfma_f32_16x16x32_bf16 v[18:21], v[170:173], v[208:211], v[18:21]
	v_mfma_f32_16x16x32_bf16 v[6:9], v[162:165], v[216:219], v[6:9]
	v_mfma_f32_16x16x32_bf16 v[2:5], v[170:173], v[216:219], v[2:5]
	v_mfma_f32_16x16x32_bf16 v[54:57], v[166:169], v[182:185], v[54:57]
	v_mfma_f32_16x16x32_bf16 v[50:53], v[174:177], v[182:185], v[50:53]
	v_mfma_f32_16x16x32_bf16 v[38:41], v[166:169], v[204:207], v[38:41]
	v_mfma_f32_16x16x32_bf16 v[34:37], v[174:177], v[204:207], v[34:37]
	v_mfma_f32_16x16x32_bf16 v[22:25], v[166:169], v[212:215], v[22:25]
	v_mfma_f32_16x16x32_bf16 v[18:21], v[174:177], v[212:215], v[18:21]
	v_mfma_f32_16x16x32_bf16 v[6:9], v[166:169], v[220:223], v[6:9]
	v_mfma_f32_16x16x32_bf16 v[2:5], v[174:177], v[220:223], v[2:5]
	s_barrier
	s_add_i32 s68, 0, 0x18000
	s_add_i32 s69, 0, 0x1c000
	v_add_u32_e32 v158, s68, v143
	v_add_u32_e32 v174, s69, v143
	ds_read_b128 v[146:149], v158
	ds_read_b128 v[150:153], v158 offset:1024
	ds_read_b128 v[154:157], v158 offset:2048
	ds_read_b128 v[158:161], v158 offset:3072
	ds_read_b128 v[162:165], v174
	ds_read_b128 v[166:169], v174 offset:1024
	ds_read_b128 v[170:173], v174 offset:2048
	ds_read_b128 v[174:177], v174 offset:3072
	s_add_u32 s50, s50, 0x80000
	s_addc_u32 s51, s51, 0
	s_mov_b32 m0, s57
	ds_read_b128 v[178:181], v145 offset:32768
	ds_read_b128 v[182:185], v145 offset:33792
	ds_read_b128 v[200:203], v145 offset:34816
	ds_read_b128 v[204:207], v145 offset:35840
	ds_read_b128 v[208:211], v145 offset:36864
	ds_read_b128 v[212:215], v145 offset:37888
	ds_read_b128 v[216:219], v145 offset:38912
	ds_read_b128 v[220:223], v145 offset:39936
	global_load_lds_dwordx4 v130, s[50:51]
	s_mov_b32 m0, s58
	s_nop 0
	global_load_lds_dwordx4 v132, s[50:51]
	s_waitcnt vmcnt(8)
	s_waitcnt lgkmcnt(0)
	s_barrier
; #define PG8_STAGE(bufoff, gbase, voff) do { _Pragma("unroll") for (int _i = 0; _i < 2; ++_i) \
;         __builtin_amdgcn_global_load_lds((const unsigned*)((const char*)(gbase) + (voff)[_i]), (LAS unsigned*)(lds + (bufoff) + ldsw + _i * 8192), 16, 0, 0); } while (0)
; #define PG8_LDA(dst, b, h) do { _Pragma("unroll") for (int m = 0; m < 4; ++m) _Pragma("unroll") for (int k = 0; k < 2; ++k) dst[m][k] = *(const LAS bf16x8*)(lds + PG8_SA(b, h) + aoff + m * 2048 + k * 1024); } while (0)
; #define PG8_MMA(ai, bj, At, Bt) do { __builtin_amdgcn_s_setprio(1); _Pragma("unroll") for (int m = 0; m < 4; ++m) _Pragma("unroll") for (int n = 0; n < 2; ++n) _Pragma("unroll") for (int k = 0; k < 2; ++k) \
;         acc[ai][bj][m][n] = __builtin_amdgcn_mfma_f32_16x16x32_bf16(Bt[n][k], At[m][k], acc[ai][bj][m][n], 0, 0, 0); __builtin_amdgcn_s_setprio(0); } while (0)
; #define PG8_WAIT_V(n) asm volatile("s_waitcnt vmcnt(" #n ")" ::: "memory")
; #define PG8_WAIT_L(n) asm volatile("s_waitcnt lgkmcnt(" #n ")" ::: "memory")
; #define PG8_BAR __builtin_amdgcn_s_barrier()
; #define PG8_SCHED __builtin_amdgcn_sched_barrier(0)
; template <class Epi, class Sched, bool ALIGN_EPI = false, bool SP2 = false>
; __device__ __forceinline__ void gemm_phase(LAS unsigned char* lds, const Gemm g, const Sched& S, const Epi& E, const int tid_) {
;     ...
;             const char* a2 = last ? nA : cA + (size_t)(t + 2) * kstep; const char* b2 = last ? nB : cB + (size_t)(t + 2) * kstep;
;     ...
;             PG8_WAIT_V(8); PG8_WAIT_L(0); PG8_BAR; PG8_MMA(0, 0, At, B0); PG8_MMA(0, 1, At, B1); PG8_BAR; PG8_SCHED;
;             PG8_LDA(At, 1, 1); PG8_STAGE(PG8_SB(1, 0), b3, voffB); PG8_STAGE(PG8_SB(1, 1), b3 + hstep, voffB); PG8_STAGE(PG8_SA(1, 0), a3, voffA);
;             PG8_WAIT_V(8); PG8_WAIT_L(0); PG8_BAR; PG8_MMA(1, 0, At, B0); PG8_MMA(1, 1, At, B1); PG8_BAR; PG8_SCHED;
	s_waitcnt lgkmcnt(0)
	v_mfma_f32_16x16x32_bf16 v[126:129], v[146:149], v[178:181], v[126:129]
	v_mfma_f32_16x16x32_bf16 v[122:125], v[154:157], v[178:181], v[122:125]
	v_mfma_f32_16x16x32_bf16 v[110:113], v[146:149], v[200:203], v[110:113]
	v_mfma_f32_16x16x32_bf16 v[106:109], v[154:157], v[200:203], v[106:109]
	v_mfma_f32_16x16x32_bf16 v[94:97], v[146:149], v[208:211], v[94:97]
	v_mfma_f32_16x16x32_bf16 v[90:93], v[154:157], v[208:211], v[90:93]
	v_mfma_f32_16x16x32_bf16 v[78:81], v[146:149], v[216:219], v[78:81]
	v_mfma_f32_16x16x32_bf16 v[74:77], v[154:157], v[216:219], v[74:77]
	v_mfma_f32_16x16x32_bf16 v[126:129], v[150:153], v[182:185], v[126:129]
	v_mfma_f32_16x16x32_bf16 v[122:125], v[158:161], v[182:185], v[122:125]
	v_mfma_f32_16x16x32_bf16 v[110:113], v[150:153], v[204:207], v[110:113]
	v_mfma_f32_16x16x32_bf16 v[106:109], v[158:161], v[204:207], v[106:109]
	v_mfma_f32_16x16x32_bf16 v[94:97], v[150:153], v[212:215], v[94:97]
	v_mfma_f32_16x16x32_bf16 v[90:93], v[158:161], v[212:215], v[90:93]
	v_mfma_f32_16x16x32_bf16 v[78:81], v[150:153], v[220:223], v[78:81]
	v_mfma_f32_16x16x32_bf16 v[74:77], v[158:161], v[220:223], v[74:77]
	v_mfma_f32_16x16x32_bf16 v[118:121], v[162:165], v[178:181], v[118:121]
	v_mfma_f32_16x16x32_bf16 v[114:117], v[170:173], v[178:181], v[114:117]
	v_mfma_f32_16x16x32_bf16 v[102:105], v[162:165], v[200:203], v[102:105]
	v_mfma_f32_16x16x32_bf16 v[98:101], v[170:173], v[200:203], v[98:101]
	v_mfma_f32_16x16x32_bf16 v[86:89], v[162:165], v[208:211], v[86:89]
	v_mfma_f32_16x16x32_bf16 v[82:85], v[170:173], v[208:211], v[82:85]
	v_mfma_f32_16x16x32_bf16 v[70:73], v[162:165], v[216:219], v[70:73]
	v_mfma_f32_16x16x32_bf16 v[66:69], v[170:173], v[216:219], v[66:69]
	v_mfma_f32_16x16x32_bf16 v[118:121], v[166:169], v[182:185], v[118:121]
	v_mfma_f32_16x16x32_bf16 v[114:117], v[174:177], v[182:185], v[114:117]
	v_mfma_f32_16x16x32_bf16 v[102:105], v[166:169], v[204:207], v[102:105]
	v_mfma_f32_16x16x32_bf16 v[98:101], v[174:177], v[204:207], v[98:101]
	v_mfma_f32_16x16x32_bf16 v[86:89], v[166:169], v[212:215], v[86:89]
	v_mfma_f32_16x16x32_bf16 v[82:85], v[174:177], v[212:215], v[82:85]
	v_mfma_f32_16x16x32_bf16 v[70:73], v[166:169], v[220:223], v[70:73]
	v_mfma_f32_16x16x32_bf16 v[66:69], v[174:177], v[220:223], v[66:69]
	s_barrier
	s_add_i32 s50, s68, s55
	s_add_i32 m0, s50, 0xffffff80
	ds_read_b128 v[178:181], v145 offset:49152
	ds_read_b128 v[182:185], v145 offset:50176
	ds_read_b128 v[200:203], v145 offset:51200
	ds_read_b128 v[204:207], v145 offset:52224
	ds_read_b128 v[208:211], v145 offset:53248
	ds_read_b128 v[212:215], v145 offset:54272
	ds_read_b128 v[216:219], v145 offset:55296
	ds_read_b128 v[220:223], v145 offset:56320
	global_load_lds_dwordx4 v0, s[48:49] offset:128
	s_add_i32 m0, s50, 0x2000
	s_add_u32 s48, s48, 0x80080
	v_lshl_add_u64 v[140:141], v[192:193], 0, s[96:97]
	s_addc_u32 s49, s49, 0
	s_add_i32 s50, s69, s55
	global_load_lds_dwordx4 v[140:141], off
	s_mov_b32 m0, s50
	s_nop 0
	global_load_lds_dwordx4 v0, s[48:49]
	s_add_i32 m0, s50, 0x2000
	s_nop 0
	global_load_lds_dwordx4 v134, s[48:49]
	v_lshl_add_u64 v[140:141], v[224:225], 0, s[96:97]
	s_mov_b32 m0, s60
	s_nop 0
	global_load_lds_dwordx4 v[140:141], off
	v_lshl_add_u64 v[140:141], v[236:237], 0, s[96:97]
	s_mov_b32 m0, s61
	s_nop 0
	global_load_lds_dwordx4 v[140:141], off
	s_waitcnt vmcnt(8)
	s_waitcnt lgkmcnt(0)
	s_barrier
	s_waitcnt lgkmcnt(0)
	v_mfma_f32_16x16x32_bf16 v[62:65], v[146:149], v[178:181], v[62:65]
	v_mfma_f32_16x16x32_bf16 v[58:61], v[154:157], v[178:181], v[58:61]
	v_mfma_f32_16x16x32_bf16 v[46:49], v[146:149], v[200:203], v[46:49]
	v_mfma_f32_16x16x32_bf16 v[42:45], v[154:157], v[200:203], v[42:45]
	s_add_i32 s67, s67, 2
	s_add_u32 s46, s46, 0x100
	s_addc_u32 s47, s47, 0
	s_add_u32 s65, s65, 0x100
	s_addc_u32 s66, s66, 0
	s_add_u32 s48, s46, 0xfff80080
	s_addc_u32 s49, s47, -1
	s_add_i32 s68, 0, 0x10000
	s_cmp_eq_u32 s67, 28
	s_cselect_b32 s51, s17, s49
	s_cselect_b32 s50, s21, s48
	s_cselect_b32 s49, s15, s66
	s_cselect_b32 s48, s64, s65
	s_add_i32 s70, 0, 0x14000
	v_mfma_f32_16x16x32_bf16 v[30:33], v[146:149], v[208:211], v[30:33]
	v_mfma_f32_16x16x32_bf16 v[26:29], v[154:157], v[208:211], v[26:29]
	v_mfma_f32_16x16x32_bf16 v[14:17], v[146:149], v[216:219], v[14:17]
	v_mfma_f32_16x16x32_bf16 v[10:13], v[154:157], v[216:219], v[10:13]
	v_mfma_f32_16x16x32_bf16 v[62:65], v[150:153], v[182:185], v[62:65]
	v_mfma_f32_16x16x32_bf16 v[58:61], v[158:161], v[182:185], v[58:61]
	v_mfma_f32_16x16x32_bf16 v[46:49], v[150:153], v[204:207], v[46:49]
	v_mfma_f32_16x16x32_bf16 v[42:45], v[158:161], v[204:207], v[42:45]
	v_mfma_f32_16x16x32_bf16 v[30:33], v[150:153], v[212:215], v[30:33]
	v_mfma_f32_16x16x32_bf16 v[26:29], v[158:161], v[212:215], v[26:29]
	v_mfma_f32_16x16x32_bf16 v[14:17], v[150:153], v[220:223], v[14:17]
	v_mfma_f32_16x16x32_bf16 v[10:13], v[158:161], v[220:223], v[10:13]
	v_mfma_f32_16x16x32_bf16 v[54:57], v[162:165], v[178:181], v[54:57]
	v_mfma_f32_16x16x32_bf16 v[50:53], v[170:173], v[178:181], v[50:53]
	v_mfma_f32_16x16x32_bf16 v[38:41], v[162:165], v[200:203], v[38:41]
	v_mfma_f32_16x16x32_bf16 v[34:37], v[170:173], v[200:203], v[34:37]
	v_mfma_f32_16x16x32_bf16 v[22:25], v[162:165], v[208:211], v[22:25]
	v_mfma_f32_16x16x32_bf16 v[18:21], v[170:173], v[208:211], v[18:21]
	v_mfma_f32_16x16x32_bf16 v[6:9], v[162:165], v[216:219], v[6:9]
	v_mfma_f32_16x16x32_bf16 v[2:5], v[170:173], v[216:219], v[2:5]
	v_mfma_f32_16x16x32_bf16 v[54:57], v[166:169], v[182:185], v[54:57]
	v_mfma_f32_16x16x32_bf16 v[50:53], v[174:177], v[182:185], v[50:53]
	v_mfma_f32_16x16x32_bf16 v[38:41], v[166:169], v[204:207], v[38:41]
	v_mfma_f32_16x16x32_bf16 v[34:37], v[174:177], v[204:207], v[34:37]
	v_mfma_f32_16x16x32_bf16 v[22:25], v[166:169], v[212:215], v[22:25]
	v_mfma_f32_16x16x32_bf16 v[18:21], v[174:177], v[212:215], v[18:21]
	v_mfma_f32_16x16x32_bf16 v[6:9], v[166:169], v[220:223], v[6:9]
	v_mfma_f32_16x16x32_bf16 v[2:5], v[174:177], v[220:223], v[2:5]
	s_barrier
	s_cmp_gt_u32 s67, 29
	s_cbranch_scc0 .LBB0_34
	s_andn2_b64 vcc, s[12:13], s[40:41]
	s_cbranch_vccz .LBB0_37
	s_barrier

; #define PG8_STAGE(bufoff, gbase, voff) do { _Pragma("unroll") for (int _i = 0; _i < 2; ++_i) \
;         __builtin_amdgcn_global_load_lds((const unsigned*)((const char*)(gbase) + (voff)[_i]), (LAS unsigned*)(lds + (bufoff) + ldsw + _i * 8192), 16, 0, 0); } while (0)
; #define PG8_LDA(dst, b, h) do { _Pragma("unroll") for (int m = 0; m < 4; ++m) _Pragma("unroll") for (int k = 0; k < 2; ++k) dst[m][k] = *(const LAS bf16x8*)(lds + PG8_SA(b, h) + aoff + m * 2048 + k * 1024); } while (0)
; #define PG8_LDB(dst, b, h) do { _Pragma("unroll") for (int n = 0; n < 2; ++n) _Pragma("unroll") for (int k = 0; k < 2; ++k) dst[n][k] = *(const LAS bf16x8*)(lds + PG8_SB(b, h) + boff + n * 2048 + k * 1024); } while (0)
; #define PG8_WAIT_V(n) asm volatile("s_waitcnt vmcnt(" #n ")" ::: "memory")
; #define PG8_WAIT_L(n) asm volatile("s_waitcnt lgkmcnt(" #n ")" ::: "memory")
; #define PG8_BAR __builtin_amdgcn_s_barrier()
; #define PG8_SCHED __builtin_amdgcn_sched_barrier(0)
; template <class Epi, class Sched, bool ALIGN_EPI = false, bool SP2 = false>
; __device__ __forceinline__ void gemm_phase(LAS unsigned char* lds, const Gemm g, const Sched& S, const Epi& E, const int tid_) {
;     ...
;         const char* nA = has_next ? (const char*)g.A + (size_t)nxt.pm * tstep : cA; const char* nB = has_next ? (const char*)g.Bt + (size_t)nxt.pn * tstep : cB;
;         for (int t = 0; t < nt; t += 2) {
;             const bool last = (t == nt - 2);
;             const char* a1 = cA + (size_t)(t + 1) * kstep;
;             const char* a2 = last ? nA : cA + (size_t)(t + 2) * kstep; const char* b2 = last ? nB : cB + (size_t)(t + 2) * kstep;
;             const char* a3 = a2 + kstep; const char* b3 = b2 + kstep;
;             if (last && has_next) S.a_ready(nxt);
;             if constexpr (SP2) {
;             PG8_LDB(B0, 0, 0); PG8_LDB(B1, 0, 1); PG8_SCHED; PG8_LDA(At, 0, 0); PG8_STAGE(PG8_SA(1, 1), a1 + hstep, voffA);
;             PG8_WAIT_V(8); PG8_WAIT_L(0); PG8_BAR; PG8_MMA(0, 0, At, B0); PG8_MMA(0, 1, At, B1); PG8_BAR; PG8_SCHED;
;     ...
;         for (int a = 0; a < 2; ++a)
; #pragma unroll
;             for (int b = 0; b < 2; ++b)
; #pragma unroll
;                 for (int m = 0; m < 4; ++m)
; #pragma unroll
;                     for (int n = 0; n < 2; ++n) acc[a][b][m][n] = (f32x4){0.f, 0.f, 0.f, 0.f};
;         cur = nxt; cA = nA; cB = nB; ++ui;
.LBB0_252:
	s_ashr_i32 s49, s48, 31
	s_lshl_b64 s[20:21], s[48:49], 20
	s_add_u32 s50, s7, s20
	s_addc_u32 s51, s29, s21
	s_and_b64 s[20:21], s[40:41], exec
	s_cselect_b32 s20, s51, s55
	s_cselect_b32 s21, s50, s54
	s_ashr_i32 s47, s46, 31
	s_lshl_b64 s[52:53], s[46:47], 20
	s_add_u32 s52, s30, s52
	s_addc_u32 s53, s31, s53
	s_and_b64 s[60:61], s[40:41], exec
	s_cselect_b32 s43, s53, s59
	s_cselect_b32 s47, s52, s58
	s_add_u32 s54, s54, 0x80080
	s_addc_u32 s55, s55, 0
	s_add_u32 s49, s58, 0x100
	v_mov_b32_e32 v2, 0
	s_addc_u32 s72, s59, 0
	s_mov_b32 s73, -2
	v_mov_b32_e32 v3, v2
	v_mov_b64_e32 v[4:5], 0
	v_mov_b64_e32 v[6:7], 0
	v_mov_b64_e32 v[8:9], 0
	v_mov_b64_e32 v[10:11], 0
	v_mov_b64_e32 v[12:13], 0
	v_mov_b64_e32 v[14:15], 0
	v_mov_b64_e32 v[16:17], 0
	v_mov_b64_e32 v[18:19], 0
	v_mov_b64_e32 v[20:21], 0
	v_mov_b64_e32 v[22:23], 0
	v_mov_b64_e32 v[24:25], 0
	v_mov_b64_e32 v[26:27], 0
	v_mov_b64_e32 v[28:29], 0
	v_mov_b64_e32 v[30:31], 0
	v_mov_b64_e32 v[32:33], 0
	v_mov_b64_e32 v[34:35], 0
	v_mov_b64_e32 v[36:37], 0
	v_mov_b64_e32 v[38:39], 0
	v_mov_b64_e32 v[40:41], 0
	v_mov_b64_e32 v[42:43], 0
	v_mov_b64_e32 v[44:45], 0
	v_mov_b64_e32 v[46:47], 0
	v_mov_b64_e32 v[48:49], 0
	v_mov_b64_e32 v[50:51], 0
	v_mov_b64_e32 v[52:53], 0
	v_mov_b64_e32 v[54:55], 0
	v_mov_b64_e32 v[56:57], 0
	v_mov_b64_e32 v[58:59], 0
	v_mov_b64_e32 v[60:61], 0
	v_mov_b64_e32 v[62:63], 0
	v_mov_b64_e32 v[64:65], 0
	v_mov_b64_e32 v[66:67], 0
	v_mov_b64_e32 v[68:69], 0
	v_mov_b64_e32 v[70:71], 0
	v_mov_b64_e32 v[72:73], 0
	v_mov_b64_e32 v[74:75], 0
	v_mov_b64_e32 v[76:77], 0
	v_mov_b64_e32 v[78:79], 0
	v_mov_b64_e32 v[80:81], 0
	v_mov_b64_e32 v[82:83], 0
	v_mov_b64_e32 v[84:85], 0
	v_mov_b64_e32 v[86:87], 0
	v_mov_b64_e32 v[88:89], 0
	v_mov_b64_e32 v[90:91], 0
	v_mov_b64_e32 v[92:93], 0
	v_mov_b64_e32 v[94:95], 0
	v_mov_b64_e32 v[96:97], 0
	v_mov_b64_e32 v[98:99], 0
	v_mov_b64_e32 v[100:101], 0
	v_mov_b64_e32 v[102:103], 0
	v_mov_b64_e32 v[104:105], 0
	v_mov_b64_e32 v[106:107], 0
	v_mov_b64_e32 v[108:109], 0
	v_mov_b64_e32 v[110:111], 0
	v_mov_b64_e32 v[112:113], 0
	v_mov_b64_e32 v[114:115], 0
	v_mov_b64_e32 v[116:117], 0
	v_mov_b64_e32 v[118:119], 0
	v_mov_b64_e32 v[120:121], 0
	v_mov_b64_e32 v[122:123], 0
	v_mov_b64_e32 v[124:125], 0
	v_mov_b64_e32 v[126:127], 0
	v_mov_b64_e32 v[128:129], 0
	s_add_u32 s58, s54, 0xfff80080
	s_addc_u32 s59, s55, -1
	s_add_i32 s74, 0, 0x10000
	s_cmp_eq_u32 s73, 28
	s_cselect_b32 s61, s20, s59
	s_cselect_b32 s60, s21, s58
	s_cselect_b32 s59, s43, s72
	s_cselect_b32 s58, s47, s49
	s_add_i32 s76, 0, 0x14000
.LBB0_253:
	v_add_u32_e32 v156, s74, v145
	v_add_u32_e32 v172, s76, v145
	ds_read_b128 v[140:143], v156
	ds_read_b128 v[148:151], v156 offset:1024
	ds_read_b128 v[152:155], v156 offset:2048
	ds_read_b128 v[156:159], v156 offset:3072
	ds_read_b128 v[160:163], v172
	ds_read_b128 v[164:167], v172 offset:1024
	ds_read_b128 v[168:171], v172 offset:2048
	ds_read_b128 v[172:175], v172 offset:3072
	s_add_i32 m0, s57, 0xc000
	ds_read_b128 v[176:179], v147
	ds_read_b128 v[180:183], v147 offset:1024
	ds_read_b128 v[200:203], v147 offset:2048
	ds_read_b128 v[204:207], v147 offset:3072
	ds_read_b128 v[208:211], v147 offset:4096
	ds_read_b128 v[212:215], v147 offset:5120
	ds_read_b128 v[216:219], v147 offset:6144
	ds_read_b128 v[220:223], v147 offset:7168
	global_load_lds_dwordx4 v136, s[54:55]
	s_add_i32 m0, s57, 0xe000
	s_nop 0
	global_load_lds_dwordx4 v138, s[54:55]
	s_waitcnt vmcnt(8)
	s_waitcnt lgkmcnt(0)
	s_barrier
	s_waitcnt lgkmcnt(0)
	v_mfma_f32_16x16x32_bf16 v[126:129], v[140:143], v[176:179], v[126:129]
	v_mfma_f32_16x16x32_bf16 v[122:125], v[152:155], v[176:179], v[122:125]
	v_mfma_f32_16x16x32_bf16 v[110:113], v[140:143], v[200:203], v[110:113]
	v_mfma_f32_16x16x32_bf16 v[106:109], v[152:155], v[200:203], v[106:109]
	v_mfma_f32_16x16x32_bf16 v[94:97], v[140:143], v[208:211], v[94:97]
	v_mfma_f32_16x16x32_bf16 v[90:93], v[152:155], v[208:211], v[90:93]
	v_mfma_f32_16x16x32_bf16 v[78:81], v[140:143], v[216:219], v[78:81]
	v_mfma_f32_16x16x32_bf16 v[74:77], v[152:155], v[216:219], v[74:77]
	v_mfma_f32_16x16x32_bf16 v[126:129], v[148:151], v[180:183], v[126:129]
	v_mfma_f32_16x16x32_bf16 v[122:125], v[156:159], v[180:183], v[122:125]
	v_mfma_f32_16x16x32_bf16 v[110:113], v[148:151], v[204:207], v[110:113]
	v_mfma_f32_16x16x32_bf16 v[106:109], v[156:159], v[204:207], v[106:109]
	v_mfma_f32_16x16x32_bf16 v[94:97], v[148:151], v[212:215], v[94:97]
	v_mfma_f32_16x16x32_bf16 v[90:93], v[156:159], v[212:215], v[90:93]
	v_mfma_f32_16x16x32_bf16 v[78:81], v[148:151], v[220:223], v[78:81]
	v_mfma_f32_16x16x32_bf16 v[74:77], v[156:159], v[220:223], v[74:77]
	v_mfma_f32_16x16x32_bf16 v[118:121], v[160:163], v[176:179], v[118:121]
	v_mfma_f32_16x16x32_bf16 v[114:117], v[168:171], v[176:179], v[114:117]
	v_mfma_f32_16x16x32_bf16 v[102:105], v[160:163], v[200:203], v[102:105]
	v_mfma_f32_16x16x32_bf16 v[98:101], v[168:171], v[200:203], v[98:101]
	v_mfma_f32_16x16x32_bf16 v[86:89], v[160:163], v[208:211], v[86:89]
	v_mfma_f32_16x16x32_bf16 v[82:85], v[168:171], v[208:211], v[82:85]
	v_mfma_f32_16x16x32_bf16 v[70:73], v[160:163], v[216:219], v[70:73]
	v_mfma_f32_16x16x32_bf16 v[66:69], v[168:171], v[216:219], v[66:69]
	v_mfma_f32_16x16x32_bf16 v[118:121], v[164:167], v[180:183], v[118:121]
	v_mfma_f32_16x16x32_bf16 v[114:117], v[172:175], v[180:183], v[114:117]
	v_mfma_f32_16x16x32_bf16 v[102:105], v[164:167], v[204:207], v[102:105]
	v_mfma_f32_16x16x32_bf16 v[98:101], v[172:175], v[204:207], v[98:101]
	v_mfma_f32_16x16x32_bf16 v[86:89], v[164:167], v[212:215], v[86:89]
	v_mfma_f32_16x16x32_bf16 v[82:85], v[172:175], v[212:215], v[82:85]
	v_mfma_f32_16x16x32_bf16 v[70:73], v[164:167], v[220:223], v[70:73]
	v_mfma_f32_16x16x32_bf16 v[66:69], v[172:175], v[220:223], v[66:69]
	s_barrier
; #define PG8_STAGE(bufoff, gbase, voff) do { _Pragma("unroll") for (int _i = 0; _i < 2; ++_i) \
;         __builtin_amdgcn_global_load_lds((const unsigned*)((const char*)(gbase) + (voff)[_i]), (LAS unsigned*)(lds + (bufoff) + ldsw + _i * 8192), 16, 0, 0); } while (0)
; #define PG8_LDA(dst, b, h) do { _Pragma("unroll") for (int m = 0; m < 4; ++m) _Pragma("unroll") for (int k = 0; k < 2; ++k) dst[m][k] = *(const LAS bf16x8*)(lds + PG8_SA(b, h) + aoff + m * 2048 + k * 1024); } while (0)
; #define PG8_LDB(dst, b, h) do { _Pragma("unroll") for (int n = 0; n < 2; ++n) _Pragma("unroll") for (int k = 0; k < 2; ++k) dst[n][k] = *(const LAS bf16x8*)(lds + PG8_SB(b, h) + boff + n * 2048 + k * 1024); } while (0)
; #define PG8_MMA(ai, bj, At, Bt) do { __builtin_amdgcn_s_setprio(1); _Pragma("unroll") for (int m = 0; m < 4; ++m) _Pragma("unroll") for (int n = 0; n < 2; ++n) _Pragma("unroll") for (int k = 0; k < 2; ++k) \
;         acc[ai][bj][m][n] = __builtin_amdgcn_mfma_f32_16x16x32_bf16(Bt[n][k], At[m][k], acc[ai][bj][m][n], 0, 0, 0); __builtin_amdgcn_s_setprio(0); } while (0)
; #define PG8_WAIT_V(n) asm volatile("s_waitcnt vmcnt(" #n ")" ::: "memory")
; #define PG8_WAIT_L(n) asm volatile("s_waitcnt lgkmcnt(" #n ")" ::: "memory")
; #define PG8_BAR __builtin_amdgcn_s_barrier()
; #define PG8_SCHED __builtin_amdgcn_sched_barrier(0)
; template <class Epi, class Sched, bool ALIGN_EPI = false, bool SP2 = false>
; __device__ __forceinline__ void gemm_phase(LAS unsigned char* lds, const Gemm g, const Sched& S, const Epi& E, const int tid_) {
;     ...
;             PG8_LDA(At, 0, 1); PG8_STAGE(PG8_SB(0, 0), b2, voffB); PG8_STAGE(PG8_SB(0, 1), b2 + hstep, voffB); PG8_STAGE(PG8_SA(0, 0), a2, voffA);
;             PG8_WAIT_V(8); PG8_WAIT_L(0); PG8_BAR; PG8_MMA(1, 0, At, B0); PG8_MMA(1, 1, At, B1); PG8_BAR; PG8_SCHED;
;             PG8_LDB(B0, 1, 0); PG8_LDB(B1, 1, 1); PG8_SCHED; PG8_LDA(At, 1, 0); PG8_STAGE(PG8_SA(0, 1), a2 + hstep, voffA);
;             PG8_WAIT_V(8); PG8_WAIT_L(0); PG8_BAR; PG8_MMA(0, 0, At, B0); PG8_MMA(0, 1, At, B1); PG8_BAR; PG8_SCHED;
;             PG8_LDA(At, 1, 1); PG8_STAGE(PG8_SB(1, 0), b3, voffB); PG8_STAGE(PG8_SB(1, 1), b3 + hstep, voffB); PG8_STAGE(PG8_SA(1, 0), a3, voffA);
	s_add_i32 s74, s74, s62
	s_mov_b32 m0, s74
	ds_read_b128 v[176:179], v147 offset:16384
	ds_read_b128 v[180:183], v147 offset:17408
	ds_read_b128 v[200:203], v147 offset:18432
	ds_read_b128 v[204:207], v147 offset:19456
	ds_read_b128 v[208:211], v147 offset:20480
	ds_read_b128 v[212:215], v147 offset:21504
	ds_read_b128 v[216:219], v147 offset:22528
	ds_read_b128 v[220:223], v147 offset:23552
	global_load_lds_dwordx4 v0, s[58:59]
	s_add_i32 m0, s74, 0x2000
	s_add_u32 s74, s58, 0x80000
	v_lshl_add_u64 v[224:225], s[58:59], 0, v[134:135]
	s_addc_u32 s75, s59, 0
	s_add_i32 s76, s76, s62
	global_load_lds_dwordx4 v134, s[58:59]
	s_mov_b32 m0, s76
	v_lshl_add_u64 v[242:243], s[60:61], 0, v[132:133]
	global_load_lds_dwordx4 v0, s[74:75]
	s_add_i32 m0, s76, 0x2000
	s_nop 0
	global_load_lds_dwordx4 v134, s[74:75]
	v_lshl_add_u64 v[236:237], s[60:61], 0, v[130:131]
	s_mov_b32 m0, s57
	s_nop 0
	global_load_lds_dwordx4 v130, s[60:61]
	s_mov_b32 m0, s63
	s_nop 0
	global_load_lds_dwordx4 v132, s[60:61]
	s_waitcnt vmcnt(8)
	s_waitcnt lgkmcnt(0)
	s_barrier
	s_waitcnt lgkmcnt(0)
	v_mfma_f32_16x16x32_bf16 v[62:65], v[140:143], v[176:179], v[62:65]
	v_mfma_f32_16x16x32_bf16 v[58:61], v[152:155], v[176:179], v[58:61]
	v_mfma_f32_16x16x32_bf16 v[46:49], v[140:143], v[200:203], v[46:49]
	v_mfma_f32_16x16x32_bf16 v[42:45], v[152:155], v[200:203], v[42:45]
	v_mfma_f32_16x16x32_bf16 v[30:33], v[140:143], v[208:211], v[30:33]
	v_mfma_f32_16x16x32_bf16 v[26:29], v[152:155], v[208:211], v[26:29]
	v_mfma_f32_16x16x32_bf16 v[14:17], v[140:143], v[216:219], v[14:17]
	v_mfma_f32_16x16x32_bf16 v[10:13], v[152:155], v[216:219], v[10:13]
	v_mfma_f32_16x16x32_bf16 v[62:65], v[148:151], v[180:183], v[62:65]
	v_mfma_f32_16x16x32_bf16 v[58:61], v[156:159], v[180:183], v[58:61]
	v_mfma_f32_16x16x32_bf16 v[46:49], v[148:151], v[204:207], v[46:49]
	v_mfma_f32_16x16x32_bf16 v[42:45], v[156:159], v[204:207], v[42:45]
	v_mfma_f32_16x16x32_bf16 v[30:33], v[148:151], v[212:215], v[30:33]
	v_mfma_f32_16x16x32_bf16 v[26:29], v[156:159], v[212:215], v[26:29]
	v_mfma_f32_16x16x32_bf16 v[14:17], v[148:151], v[220:223], v[14:17]
	v_mfma_f32_16x16x32_bf16 v[10:13], v[156:159], v[220:223], v[10:13]
	v_mfma_f32_16x16x32_bf16 v[54:57], v[160:163], v[176:179], v[54:57]
	v_mfma_f32_16x16x32_bf16 v[50:53], v[168:171], v[176:179], v[50:53]
	v_mfma_f32_16x16x32_bf16 v[38:41], v[160:163], v[200:203], v[38:41]
	v_mfma_f32_16x16x32_bf16 v[34:37], v[168:171], v[200:203], v[34:37]
	v_mfma_f32_16x16x32_bf16 v[22:25], v[160:163], v[208:211], v[22:25]
	v_mfma_f32_16x16x32_bf16 v[18:21], v[168:171], v[208:211], v[18:21]
	v_mfma_f32_16x16x32_bf16 v[6:9], v[160:163], v[216:219], v[6:9]
	v_mfma_f32_16x16x32_bf16 v[2:5], v[168:171], v[216:219], v[2:5]
	v_mfma_f32_16x16x32_bf16 v[54:57], v[164:167], v[180:183], v[54:57]
	v_mfma_f32_16x16x32_bf16 v[50:53], v[172:175], v[180:183], v[50:53]
	v_mfma_f32_16x16x32_bf16 v[38:41], v[164:167], v[204:207], v[38:41]
	v_mfma_f32_16x16x32_bf16 v[34:37], v[172:175], v[204:207], v[34:37]
	v_mfma_f32_16x16x32_bf16 v[22:25], v[164:167], v[212:215], v[22:25]
	v_mfma_f32_16x16x32_bf16 v[18:21], v[172:175], v[212:215], v[18:21]
	v_mfma_f32_16x16x32_bf16 v[6:9], v[164:167], v[220:223], v[6:9]
	v_mfma_f32_16x16x32_bf16 v[2:5], v[172:175], v[220:223], v[2:5]
	s_barrier
	s_add_i32 s74, 0, 0x18000
	s_add_i32 s75, 0, 0x1c000
	v_add_u32_e32 v156, s74, v145
	v_add_u32_e32 v172, s75, v145
	ds_read_b128 v[140:143], v156
	ds_read_b128 v[148:151], v156 offset:1024
	ds_read_b128 v[152:155], v156 offset:2048
	ds_read_b128 v[156:159], v156 offset:3072
	ds_read_b128 v[160:163], v172
	ds_read_b128 v[164:167], v172 offset:1024
	ds_read_b128 v[168:171], v172 offset:2048
	ds_read_b128 v[172:175], v172 offset:3072
	s_add_u32 s60, s60, 0x80000
	s_addc_u32 s61, s61, 0
	s_mov_b32 m0, s64
	ds_read_b128 v[176:179], v147 offset:32768
	ds_read_b128 v[180:183], v147 offset:33792
	ds_read_b128 v[200:203], v147 offset:34816
	ds_read_b128 v[204:207], v147 offset:35840
	ds_read_b128 v[208:211], v147 offset:36864
	ds_read_b128 v[212:215], v147 offset:37888
	ds_read_b128 v[216:219], v147 offset:38912
	ds_read_b128 v[220:223], v147 offset:39936
	global_load_lds_dwordx4 v130, s[60:61]
	s_mov_b32 m0, s65
	s_nop 0
	global_load_lds_dwordx4 v132, s[60:61]
	s_waitcnt vmcnt(8)
	s_waitcnt lgkmcnt(0)
	s_barrier
; #define PG8_STAGE(bufoff, gbase, voff) do { _Pragma("unroll") for (int _i = 0; _i < 2; ++_i) \
;         __builtin_amdgcn_global_load_lds((const unsigned*)((const char*)(gbase) + (voff)[_i]), (LAS unsigned*)(lds + (bufoff) + ldsw + _i * 8192), 16, 0, 0); } while (0)
; #define PG8_LDA(dst, b, h) do { _Pragma("unroll") for (int m = 0; m < 4; ++m) _Pragma("unroll") for (int k = 0; k < 2; ++k) dst[m][k] = *(const LAS bf16x8*)(lds + PG8_SA(b, h) + aoff + m * 2048 + k * 1024); } while (0)
; #define PG8_MMA(ai, bj, At, Bt) do { __builtin_amdgcn_s_setprio(1); _Pragma("unroll") for (int m = 0; m < 4; ++m) _Pragma("unroll") for (int n = 0; n < 2; ++n) _Pragma("unroll") for (int k = 0; k < 2; ++k) \
;         acc[ai][bj][m][n] = __builtin_amdgcn_mfma_f32_16x16x32_bf16(Bt[n][k], At[m][k], acc[ai][bj][m][n], 0, 0, 0); __builtin_amdgcn_s_setprio(0); } while (0)
; #define PG8_WAIT_V(n) asm volatile("s_waitcnt vmcnt(" #n ")" ::: "memory")
; #define PG8_WAIT_L(n) asm volatile("s_waitcnt lgkmcnt(" #n ")" ::: "memory")
; #define PG8_BAR __builtin_amdgcn_s_barrier()
; #define PG8_SCHED __builtin_amdgcn_sched_barrier(0)
; template <class Epi, class Sched, bool ALIGN_EPI = false, bool SP2 = false>
; __device__ __forceinline__ void gemm_phase(LAS unsigned char* lds, const Gemm g, const Sched& S, const Epi& E, const int tid_) {
;     ...
;             const char* a2 = last ? nA : cA + (size_t)(t + 2) * kstep; const char* b2 = last ? nB : cB + (size_t)(t + 2) * kstep;
;     ...
;             PG8_WAIT_V(8); PG8_WAIT_L(0); PG8_BAR; PG8_MMA(0, 0, At, B0); PG8_MMA(0, 1, At, B1); PG8_BAR; PG8_SCHED;
;             PG8_LDA(At, 1, 1); PG8_STAGE(PG8_SB(1, 0), b3, voffB); PG8_STAGE(PG8_SB(1, 1), b3 + hstep, voffB); PG8_STAGE(PG8_SA(1, 0), a3, voffA);
;             PG8_WAIT_V(8); PG8_WAIT_L(0); PG8_BAR; PG8_MMA(1, 0, At, B0); PG8_MMA(1, 1, At, B1); PG8_BAR; PG8_SCHED;
	s_waitcnt lgkmcnt(0)
	v_mfma_f32_16x16x32_bf16 v[126:129], v[140:143], v[176:179], v[126:129]
	v_mfma_f32_16x16x32_bf16 v[122:125], v[152:155], v[176:179], v[122:125]
	v_mfma_f32_16x16x32_bf16 v[110:113], v[140:143], v[200:203], v[110:113]
	v_mfma_f32_16x16x32_bf16 v[106:109], v[152:155], v[200:203], v[106:109]
	v_mfma_f32_16x16x32_bf16 v[94:97], v[140:143], v[208:211], v[94:97]
	v_mfma_f32_16x16x32_bf16 v[90:93], v[152:155], v[208:211], v[90:93]
	v_mfma_f32_16x16x32_bf16 v[78:81], v[140:143], v[216:219], v[78:81]
	v_mfma_f32_16x16x32_bf16 v[74:77], v[152:155], v[216:219], v[74:77]
	v_mfma_f32_16x16x32_bf16 v[126:129], v[148:151], v[180:183], v[126:129]
	v_mfma_f32_16x16x32_bf16 v[122:125], v[156:159], v[180:183], v[122:125]
	v_mfma_f32_16x16x32_bf16 v[110:113], v[148:151], v[204:207], v[110:113]
	v_mfma_f32_16x16x32_bf16 v[106:109], v[156:159], v[204:207], v[106:109]
	v_mfma_f32_16x16x32_bf16 v[94:97], v[148:151], v[212:215], v[94:97]
	v_mfma_f32_16x16x32_bf16 v[90:93], v[156:159], v[212:215], v[90:93]
	v_mfma_f32_16x16x32_bf16 v[78:81], v[148:151], v[220:223], v[78:81]
	v_mfma_f32_16x16x32_bf16 v[74:77], v[156:159], v[220:223], v[74:77]
	v_mfma_f32_16x16x32_bf16 v[118:121], v[160:163], v[176:179], v[118:121]
	v_mfma_f32_16x16x32_bf16 v[114:117], v[168:171], v[176:179], v[114:117]
	v_mfma_f32_16x16x32_bf16 v[102:105], v[160:163], v[200:203], v[102:105]
	v_mfma_f32_16x16x32_bf16 v[98:101], v[168:171], v[200:203], v[98:101]
	v_mfma_f32_16x16x32_bf16 v[86:89], v[160:163], v[208:211], v[86:89]
	v_mfma_f32_16x16x32_bf16 v[82:85], v[168:171], v[208:211], v[82:85]
	v_mfma_f32_16x16x32_bf16 v[70:73], v[160:163], v[216:219], v[70:73]
	v_mfma_f32_16x16x32_bf16 v[66:69], v[168:171], v[216:219], v[66:69]
	v_mfma_f32_16x16x32_bf16 v[118:121], v[164:167], v[180:183], v[118:121]
	v_mfma_f32_16x16x32_bf16 v[114:117], v[172:175], v[180:183], v[114:117]
	v_mfma_f32_16x16x32_bf16 v[102:105], v[164:167], v[204:207], v[102:105]
	v_mfma_f32_16x16x32_bf16 v[98:101], v[172:175], v[204:207], v[98:101]
	v_mfma_f32_16x16x32_bf16 v[86:89], v[164:167], v[212:215], v[86:89]
	v_mfma_f32_16x16x32_bf16 v[82:85], v[172:175], v[212:215], v[82:85]
	v_mfma_f32_16x16x32_bf16 v[70:73], v[164:167], v[220:223], v[70:73]
	v_mfma_f32_16x16x32_bf16 v[66:69], v[172:175], v[220:223], v[66:69]
	s_barrier
	s_add_i32 s60, s74, s62
	s_add_i32 m0, s60, 0xffffff80
	ds_read_b128 v[176:179], v147 offset:49152
	ds_read_b128 v[180:183], v147 offset:50176
	ds_read_b128 v[200:203], v147 offset:51200
	ds_read_b128 v[204:207], v147 offset:52224
	ds_read_b128 v[208:211], v147 offset:53248
	ds_read_b128 v[212:215], v147 offset:54272
	ds_read_b128 v[216:219], v147 offset:55296
	ds_read_b128 v[220:223], v147 offset:56320
	global_load_lds_dwordx4 v0, s[58:59] offset:128
	s_add_i32 m0, s60, 0x2000
	s_add_u32 s58, s58, 0x80080
	v_lshl_add_u64 v[184:185], v[224:225], 0, s[96:97]
	s_addc_u32 s59, s59, 0
	s_add_i32 s60, s75, s62
	global_load_lds_dwordx4 v[184:185], off
	s_mov_b32 m0, s60
	s_nop 0
	global_load_lds_dwordx4 v0, s[58:59]
	s_add_i32 m0, s60, 0x2000
	s_nop 0
	global_load_lds_dwordx4 v134, s[58:59]
	v_lshl_add_u64 v[184:185], v[236:237], 0, s[96:97]
	s_mov_b32 m0, s67
	s_nop 0
	global_load_lds_dwordx4 v[184:185], off
	v_lshl_add_u64 v[184:185], v[242:243], 0, s[96:97]
	s_mov_b32 m0, s68
	s_nop 0
	global_load_lds_dwordx4 v[184:185], off
	s_waitcnt vmcnt(8)
	s_waitcnt lgkmcnt(0)
	s_barrier
	s_waitcnt lgkmcnt(0)
	v_mfma_f32_16x16x32_bf16 v[62:65], v[140:143], v[176:179], v[62:65]
	v_mfma_f32_16x16x32_bf16 v[58:61], v[152:155], v[176:179], v[58:61]
	v_mfma_f32_16x16x32_bf16 v[46:49], v[140:143], v[200:203], v[46:49]
	v_mfma_f32_16x16x32_bf16 v[42:45], v[152:155], v[200:203], v[42:45]
	s_add_i32 s73, s73, 2
	s_add_u32 s54, s54, 0x100
	s_addc_u32 s55, s55, 0
	s_add_u32 s49, s49, 0x100
	s_addc_u32 s72, s72, 0
	s_add_u32 s58, s54, 0xfff80080
	s_addc_u32 s59, s55, -1
	s_add_i32 s74, 0, 0x10000
	s_cmp_eq_u32 s73, 28
	s_cselect_b32 s61, s20, s59
	s_cselect_b32 s60, s21, s58
	s_cselect_b32 s59, s43, s72
	s_cselect_b32 s58, s47, s49
	s_add_i32 s76, 0, 0x14000
	v_mfma_f32_16x16x32_bf16 v[30:33], v[140:143], v[208:211], v[30:33]
	v_mfma_f32_16x16x32_bf16 v[26:29], v[152:155], v[208:211], v[26:29]
	v_mfma_f32_16x16x32_bf16 v[14:17], v[140:143], v[216:219], v[14:17]
	v_mfma_f32_16x16x32_bf16 v[10:13], v[152:155], v[216:219], v[10:13]
	v_mfma_f32_16x16x32_bf16 v[62:65], v[148:151], v[180:183], v[62:65]
	v_mfma_f32_16x16x32_bf16 v[58:61], v[156:159], v[180:183], v[58:61]
	v_mfma_f32_16x16x32_bf16 v[46:49], v[148:151], v[204:207], v[46:49]
	v_mfma_f32_16x16x32_bf16 v[42:45], v[156:159], v[204:207], v[42:45]
	v_mfma_f32_16x16x32_bf16 v[30:33], v[148:151], v[212:215], v[30:33]
	v_mfma_f32_16x16x32_bf16 v[26:29], v[156:159], v[212:215], v[26:29]
	v_mfma_f32_16x16x32_bf16 v[14:17], v[148:151], v[220:223], v[14:17]
	v_mfma_f32_16x16x32_bf16 v[10:13], v[156:159], v[220:223], v[10:13]
	v_mfma_f32_16x16x32_bf16 v[54:57], v[160:163], v[176:179], v[54:57]
	v_mfma_f32_16x16x32_bf16 v[50:53], v[168:171], v[176:179], v[50:53]
	v_mfma_f32_16x16x32_bf16 v[38:41], v[160:163], v[200:203], v[38:41]
	v_mfma_f32_16x16x32_bf16 v[34:37], v[168:171], v[200:203], v[34:37]
	v_mfma_f32_16x16x32_bf16 v[22:25], v[160:163], v[208:211], v[22:25]
	v_mfma_f32_16x16x32_bf16 v[18:21], v[168:171], v[208:211], v[18:21]
	v_mfma_f32_16x16x32_bf16 v[6:9], v[160:163], v[216:219], v[6:9]
	v_mfma_f32_16x16x32_bf16 v[2:5], v[168:171], v[216:219], v[2:5]
	v_mfma_f32_16x16x32_bf16 v[54:57], v[164:167], v[180:183], v[54:57]
	v_mfma_f32_16x16x32_bf16 v[50:53], v[172:175], v[180:183], v[50:53]
	v_mfma_f32_16x16x32_bf16 v[38:41], v[164:167], v[204:207], v[38:41]
	v_mfma_f32_16x16x32_bf16 v[34:37], v[172:175], v[204:207], v[34:37]
	v_mfma_f32_16x16x32_bf16 v[22:25], v[164:167], v[212:215], v[22:25]
	v_mfma_f32_16x16x32_bf16 v[18:21], v[172:175], v[212:215], v[18:21]
	v_mfma_f32_16x16x32_bf16 v[6:9], v[164:167], v[220:223], v[6:9]
	v_mfma_f32_16x16x32_bf16 v[2:5], v[172:175], v[220:223], v[2:5]
	s_barrier
	s_cmp_gt_u32 s73, 29
	s_cbranch_scc0 .LBB0_253
	s_andn2_b64 vcc, s[10:11], s[40:41]
	s_cbranch_vccz .LBB0_256
	s_barrier
